# compressed-branch passes staged HBM->LDS directly as well (same per-lane source permutation); on top of v31
# speedup vs baseline: 1.0287x; 1.0098x over previous
; template <int STG, class F>
; __device__ __forceinline__ void stream_tiles(Ctx& C, const TileSrc& src, int tile0, int ntiles, LAS unsigned char* bufs, F&& compute) {
;     if (ntiles <= 0) return;
;     const int nst = (ntiles + STG - 1) / STG, tlast = tile0 + ntiles - 1;
;     v4u rk[STG], rv[STG];
;     { const int tidl = launder_v(C.tid);
; #pragma unroll
;       for (int h = 0; h < STG; ++h) { const int t = tile0 + h; tile_fetch(src, 64 * (t < tlast ? t : tlast), tidl, rk[h], rv[h]); }
; #pragma unroll
;       for (int h = 0; h < STG; ++h) tile_store(bufs + h * 16384, tidl, rk[h], rv[h]); }
;     __syncthreads();
; #pragma unroll 1
;     for (int st = 0; st < nst; ++st) {
;         const int tidl = launder_v(C.tid);
;         const bool more = st + 1 < nst;
;         if (more) {
; #pragma unroll
;             for (int h = 0; h < STG; ++h) { const int t = tile0 + STG * (st + 1) + h; tile_fetch(src, 64 * (t < tlast ? t : tlast), tidl, rk[h], rv[h]); } }
; __device__ __forceinline__ void nsa_block_task(Ctx& C, int task, bf16* ONSA_OUT) {
;     const int lane = C.lane, r = lane & 15, fq = lane >> 4, qi = r >> 2, g = r & 3, w = C.wave;
;     const int kvh = task >= 256 ? 1 : 0, qb = task >= 256 ? 511 - task : task, t0 = 64 * qb;
;     LAS unsigned char* bufs = C.lds;
;     LAS float* SC = (LAS float*)(C.lds + 65536 + w * 8448);
;     LAS unsigned* SELM = (LAS unsigned*)(C.lds + 133120 + w * 256);
;     const int head = kvh * 4 + g;
;     int tl[2]; bf16x8 bq[2][2]; float g_c[2], g_s[2], g_w[2];
; #pragma unroll
;     for (int cg = 0; cg < 2; ++cg) { tl[cg] = t0 + 8 * w + 4 * cg + qi;
;         const bf16* qp = WSP(bf16, WS_Q) + ((size_t)tl[cg] * 8 + head) * 64 + 8 * fq; bq[cg][0] = *(const bf16x8*)qp; bq[cg][1] = *(const bf16x8*)(qp + 32);
;         const float* gn = WSP(float, WS_GN) + (size_t)tl[cg] * 24 + head * 3; g_c[cg] = gn[0]; g_s[cg] = gn[1]; g_w[cg] = gn[2]; }
;     f4 oc[2][4];
;     {
;         const int kvc = launder_s(kvh);
;         const TileSrc src{WSP(bf16, WS_CMPKP) + (size_t)kvc * 65536, WSP(bf16, WS_CMPVP) + (size_t)kvc * 65536, 1024};
;         int nvis[2];
; #pragma unroll
;         for (int cg = 0; cg < 2; ++cg) nvis[cg] = tl[cg] >= 31 ? ((tl[cg] - 31) >> 4) + 1 : 0;
;         const int twmax = t0 + 8 * w + 7; const int nvw = twmax >= 31 ? ((twmax - 31) >> 4) + 1 : 0;
;         const int nvb = ((t0 + 63 - 31) >> 4) + 1;
.LBB0_1115:
	s_or_b64 exec, exec, s[16:17]
	s_waitcnt vmcnt(0) lgkmcnt(0)
	s_barrier
	ds_read_b32 v0, v229
	s_movk_i32 s16, 0x1ff
	s_waitcnt lgkmcnt(0)
	s_barrier
	v_cmp_lt_u32_e32 vcc, s16, v0
	v_readfirstlane_b32 s0, v0
	s_mov_b64 s[16:17], -1
	s_cbranch_vccnz .LBB0_1112
	s_lshr_b32 s16, s0, 1
	s_sub_i32 s17, 0xff, s16
	s_and_b32 s97, s0, 1
	s_xor_b32 s0, s16, 0xff
	s_cmp_eq_u32 s97, 0
	s_cselect_b32 s94, s17, s0
	v_lshl_or_b32 v38, s97, 2, v221
	s_lshl_b32 s54, s94, 6
	v_lshlrev_b32_e32 v0, 7, v38
	s_add_i32 s95, s65, s54
	v_lshl_add_u64 v[2:3], v[196:197], 0, v[0:1]
	v_mul_u32_u24_e32 v0, 3, v38
	v_or_b32_e32 v216, s95, v199
	v_lshlrev_b32_e32 v0, 2, v0
	v_lshl_add_u64 v[16:17], s[52:53], 0, v[0:1]
	v_mov_b32_e32 v217, v1
	v_or_b32_e32 v218, 4, v216
	v_mov_b32_e32 v219, v1
	v_lshlrev_b64 v[214:215], 10, v[216:217]
	v_mad_u64_u32 v[12:13], s[16:17], v216, s90, v[16:17]
	v_lshlrev_b64 v[212:213], 10, v[218:219]
	v_mad_u64_u32 v[20:21], s[16:17], v218, s90, v[16:17]
	v_lshl_add_u64 v[8:9], v[2:3], 0, v[214:215]
	v_lshl_add_u64 v[2:3], v[2:3], 0, v[212:213]
	s_mov_b32 s16, s97
	global_load_dwordx4 v[4:7], v[8:9], off
	s_nop 0
	global_load_dwordx4 v[8:11], v[8:9], off offset:64
	s_nop 0
	global_load_dwordx3 v[186:188], v[12:13], off
	s_nop 0
	global_load_dwordx4 v[12:15], v[2:3], off
	global_load_dwordx4 v[16:19], v[2:3], off offset:64
	global_load_dwordx3 v[182:184], v[20:21], off
	s_ashr_i32 s17, s16, 31
	s_lshl_b64 s[16:17], s[16:17], 17
	s_add_u32 s20, s74, s16
	s_addc_u32 s21, s75, s17
	s_add_u32 s22, s72, s16
	s_addc_u32 s23, s73, s17
	s_sub_i32 s0, s95, 24
	s_ashr_i32 s0, s0, 4
	s_or_b32 s96, s95, 7
	s_add_i32 s0, s0, 1
	s_cmp_gt_u32 s96, 30
	s_cselect_b32 s0, s0, 0
	s_lshl_b32 s16, s94, 2
	s_addk_i32 s16, 0x42
	s_lshr_b32 s26, s16, 6
	s_add_i32 s16, s26, 1
	s_add_i32 s27, s26, -1
	v_mov_b32_e32 v39, v189
	s_cmp_eq_u32 s27, 0
	v_ashrrev_i32_e32 v36, 3, v39
	v_ashrrev_i32_e32 v37, 31, v36
	s_cselect_b32 s29, 0, 64
	v_lshlrev_b32_e32 v40, 4, v39
	v_lshlrev_b64 v[20:21], 11, v[36:37]
	v_add_u32_e32 v30, s29, v36
	v_and_b32_e32 v0, 0x70, v40
	v_lshl_add_u64 v[20:21], s[22:23], 0, v[20:21]
	v_ashrrev_i32_e32 v31, 31, v30
	v_lshl_add_u64 v[2:3], s[20:21], 0, v[0:1]
	v_lshl_add_u64 v[28:29], v[20:21], 0, v[0:1]
	v_lshlrev_b64 v[20:21], 7, v[36:37]
	v_lshlrev_b64 v[30:31], 7, v[30:31]
	s_lshl_b32 s50, s29, 1
	v_lshl_add_u64 v[20:21], v[2:3], 0, v[20:21]
	v_lshl_add_u64 v[2:3], v[2:3], 0, v[30:31]
	v_lshl_add_u64 v[32:33], v[28:29], 0, s[50:51]
	v_lshrrev_b32_e32 v233, 3, v189
	v_and_b32_e32 v254, 7, v189
	v_bfe_u32 v174, v233, 1, 3
	v_xor_b32_e32 v254, v254, v174
	v_lshlrev_b32_e32 v254, 4, v254
	v_lshl_add_u32 v198, v233, 11, v254
	v_and_b32_e32 v174, 32, v233
	v_bfe_u32 v175, v233, 2, 2
	v_lshl_or_b32 v174, v175, 3, v174
	v_bfe_u32 v175, v233, 4, 1
	v_lshl_or_b32 v174, v175, 2, v174
	v_and_or_b32 v174, v233, 3, v174
	v_lshl_add_u32 v185, v174, 7, v254
	v_readfirstlane_b32 s44, v189
	s_lshl_b32 s44, s44, 4
	s_mov_b32 s45, s44
	s_mov_b32 s36, 0
	s_add_i32 m0, s45, 0x0
	s_lshl_b32 s98, s36, 13
	s_add_u32 s98, s20, s98
	s_addc_u32 s99, s21, 0
	global_load_lds_dwordx4 v185, s[98:99]
	s_add_i32 m0, s45, 0x2000
	s_lshl_b32 s100, s36, 7
	s_add_u32 s100, s22, s100
	s_addc_u32 s101, s23, 0
	global_load_lds_dwordx4 v198, s[100:101]
	s_min_i32 s36, 1, s27
	s_add_i32 m0, s45, 0x4000
	s_lshl_b32 s98, s36, 13
	s_add_u32 s98, s20, s98
	s_addc_u32 s99, s21, 0
	global_load_lds_dwordx4 v185, s[98:99]
	s_add_i32 m0, s45, 0x6000
	s_lshl_b32 s100, s36, 7
	s_add_u32 s100, s22, s100
	s_addc_u32 s101, s23, 0
	global_load_lds_dwordx4 v198, s[100:101]
	v_subrev_u32_e32 v0, 31, v216
	v_subrev_u32_e32 v3, 27, v216
	v_lshrrev_b32_e32 v0, 4, v0
	v_lshrrev_b32_e32 v3, 4, v3
	v_add_u32_e32 v0, 1, v0
	v_cmp_lt_u32_e32 vcc, 30, v216
	v_add_u32_e32 v3, 1, v3
	v_and_b32_e32 v37, 35, v36
	v_cndmask_b32_e32 v72, 0, v0, vcc
	v_cmp_lt_u32_e32 vcc, 30, v218
	v_lshlrev_b32_e32 v0, 2, v36
	v_and_b32_e32 v0, 16, v0
	v_cndmask_b32_e32 v73, 0, v3, vcc
	v_lshrrev_b32_e32 v3, 1, v36
	v_and_b32_e32 v3, 12, v3
	v_or3_b32 v0, v0, v37, v3
	v_lshlrev_b32_e32 v3, 7, v0
	v_lshrrev_b32_e32 v0, 1, v0
	v_xor_b32_e32 v0, v0, v39
	v_lshlrev_b32_e32 v0, 4, v0
	v_mov_b32_e32 v2, 0
	v_and_b32_e32 v0, 0x70, v0
	s_mov_b32 s18, 0
	v_lshlrev_b32_e32 v220, 6, v38
	v_lshlrev_b32_e32 v36, 7, v36
	v_bitop3_b32 v38, v40, s91, v39 bitop3:0x48
	v_add3_u32 v0, 0, v3, v0
	s_lshr_b32 s28, s16, 1
	v_mov_b32_e32 v74, 0xf149f2ca
	v_mov_b32_e32 v75, 0xf149f2ca
	v_mov_b32_e32 v3, v2
	v_add3_u32 v36, 0, v36, v38
	s_waitcnt vmcnt(0) lgkmcnt(0)
	s_waitcnt lgkmcnt(0)
	s_barrier
.LBB0_1117:
	s_add_i32 s30, s18, 1
	s_cmp_lt_u32 s30, s28
	v_mov_b32_e32 v60, v189
	s_cselect_b64 s[16:17], -1, 0
	s_cmp_ge_u32 s30, s28
	s_cbranch_scc1 .LBB0_1119
	s_lshl_b32 s19, s30, 1
	s_lshl_b32 s37, s30, 15
	s_and_b32 s37, s37, 0x8000
	s_add_i32 s45, s37, s44
	s_min_i32 s36, s19, s27
	s_add_i32 m0, s45, 0x0
	s_lshl_b32 s98, s36, 13
	s_add_u32 s98, s20, s98
	s_addc_u32 s99, s21, 0
	global_load_lds_dwordx4 v185, s[98:99]
	s_add_i32 m0, s45, 0x2000
	s_lshl_b32 s100, s36, 7
	s_add_u32 s100, s22, s100
	s_addc_u32 s101, s23, 0
	global_load_lds_dwordx4 v198, s[100:101]
	s_add_i32 s36, s19, 1
	s_min_i32 s36, s36, s27
	s_add_i32 m0, s45, 0x4000
	s_lshl_b32 s98, s36, 13
	s_add_u32 s98, s20, s98
	s_addc_u32 s99, s21, 0
	global_load_lds_dwordx4 v185, s[98:99]
	s_add_i32 m0, s45, 0x6000
	s_lshl_b32 s100, s36, 7
	s_add_u32 s100, s22, s100
	s_addc_u32 s101, s23, 0
	global_load_lds_dwordx4 v198, s[100:101]

; template <int STG, class F>
; __device__ __forceinline__ void stream_tiles(Ctx& C, const TileSrc& src, int tile0, int ntiles, LAS unsigned char* bufs, F&& compute) {
;     ...
;         if (more) {
; #pragma unroll
;             for (int h = 0; h < STG; ++h) tile_store(bufs + ((st + 1) & 1) * (STG * 16384) + h * 16384, tidl, rk[h], rv[h]); }
;         __syncthreads();
.LBB0_1134:
	s_andn2_b64 vcc, exec, s[16:17]
	s_cbranch_vccnz .LBB0_1136
	s_waitcnt vmcnt(0) lgkmcnt(0)

; #define LAS __attribute__((address_space(3)))
; __device__ __forceinline__ int launder_v(int x) { asm volatile("" : "+v"(x)); return x; }
; #define WAVE_SYNC() do { __builtin_amdgcn_wave_barrier(); asm volatile("s_waitcnt lgkmcnt(0)" ::: "memory"); __builtin_amdgcn_wave_barrier(); } while (0)
; __device__ __forceinline__ float col_total(float l) { l += __shfl_xor(l, 16); l += __shfl_xor(l, 32); return l; }
; template <int STG, class F>
; __device__ __forceinline__ void stream_tiles(Ctx& C, const TileSrc& src, int tile0, int ntiles, LAS unsigned char* bufs, F&& compute) {
;     ...
;     const int nst = (ntiles + STG - 1) / STG, tlast = tile0 + ntiles - 1;
;     v4u rk[STG], rv[STG];
;     { const int tidl = launder_v(C.tid);
; #pragma unroll
;       for (int h = 0; h < STG; ++h) { const int t = tile0 + h; tile_fetch(src, 64 * (t < tlast ? t : tlast), tidl, rk[h], rv[h]); }
; #pragma unroll
;       for (int h = 0; h < STG; ++h) tile_store(bufs + h * 16384, tidl, rk[h], rv[h]); }
;     __syncthreads();
; #pragma unroll 1
;     for (int st = 0; st < nst; ++st) {
;         const int tidl = launder_v(C.tid);
;         const bool more = st + 1 < nst;
;         if (more) {
; #pragma unroll
;             for (int h = 0; h < STG; ++h) { const int t = tile0 + STG * (st + 1) + h; tile_fetch(src, 64 * (t < tlast ? t : tlast), tidl, rk[h], rv[h]); } }
; __device__ __forceinline__ void nsa_block_task(Ctx& C, int task, bf16* ONSA_OUT) {
;     ...
;         float il[2];
; #pragma unroll
;         for (int cg = 0; cg < 2; ++cg) { const float lt = col_total(l[cg]); il[cg] = lt > 0.f ? 1.0f / lt : 0.f; }
; #pragma unroll
;         for (int i = 0; i < 32; ++i) SC[lane * 32 + i] = 0.f;
;         WAVE_SYNC();
;         f4 o[2][4];
; #pragma unroll
;         for (int cg = 0; cg < 2; ++cg)
; #pragma unroll
;             for (int c = 0; c < 4; ++c) o[cg][c] = (f4){0.f, 0.f, 0.f, 0.f};
;         float tprev[2] = {0.f, 0.f};
;         stream_tiles<2>(C, src, 0, ntile, bufs, [&](const LAS unsigned char* buf, int j) {
.LBB0_1138:
	s_mov_b32 s16, 0
	s_mov_b32 s18, s16
	s_mov_b32 s19, s16
	s_mov_b32 s17, s16
	s_waitcnt vmcnt(0)
	v_mov_b64_e32 v[22:23], s[18:19]
	v_mov_b64_e32 v[20:21], s[16:17]
	v_mov_b32_e32 v28, v189
	ds_write_b128 v230, v[20:23]
	ds_write_b128 v230, v[20:23] offset:16
	ds_write_b128 v230, v[20:23] offset:32
	ds_write_b128 v230, v[20:23] offset:48
	ds_write_b128 v230, v[20:23] offset:64
	ds_write_b128 v230, v[20:23] offset:80
	ds_write_b128 v230, v[20:23] offset:96
	ds_write_b128 v230, v[20:23] offset:112
	s_waitcnt lgkmcnt(0)
	v_mov_b32_e32 v23, v1
	v_ashrrev_i32_e32 v20, 3, v28
	v_ashrrev_i32_e32 v21, 31, v20
	v_lshlrev_b32_e32 v29, 4, v28
	v_lshlrev_b64 v[26:27], 11, v[20:21]
	v_and_b32_e32 v22, 0x70, v29
	v_lshl_add_u64 v[26:27], s[22:23], 0, v[26:27]
	v_lshl_add_u64 v[24:25], s[20:21], 0, v[22:23]
	v_lshl_add_u64 v[22:23], v[26:27], 0, v[22:23]
	v_lshlrev_b64 v[26:27], 7, v[20:21]
	v_lshl_add_u64 v[26:27], v[24:25], 0, v[26:27]
	s_mov_b32 s45, s44
	s_mov_b32 s36, 0
	s_add_i32 m0, s45, 0x0
	s_lshl_b32 s98, s36, 13
	s_add_u32 s98, s20, s98
	s_addc_u32 s99, s21, 0
	global_load_lds_dwordx4 v185, s[98:99]
	s_add_i32 m0, s45, 0x2000
	s_lshl_b32 s100, s36, 7
	s_add_u32 s100, s22, s100
	s_addc_u32 s101, s23, 0
	global_load_lds_dwordx4 v198, s[100:101]
	s_min_i32 s36, 1, s27
	s_add_i32 m0, s45, 0x4000
	s_lshl_b32 s98, s36, 13
	s_add_u32 s98, s20, s98
	s_addc_u32 s99, s21, 0
	global_load_lds_dwordx4 v185, s[98:99]
	s_add_i32 m0, s45, 0x6000
	s_lshl_b32 s100, s36, 7
	s_add_u32 s100, s22, s100
	s_addc_u32 s101, s23, 0
	global_load_lds_dwordx4 v198, s[100:101]
	v_add_u32_e32 v26, s29, v20
	v_ashrrev_i32_e32 v27, 31, v26
	v_lshlrev_b64 v[26:27], 7, v[26:27]
	v_lshl_add_u64 v[24:25], v[24:25], 0, v[26:27]
	s_lshl_b32 s50, s29, 1
	v_lshl_add_u64 v[22:23], v[22:23], 0, s[50:51]
	v_and_b32_e32 v76, 64, v191
	v_xor_b32_e32 v0, 16, v191
	v_add_u32_e32 v21, 64, v76
	v_cmp_lt_i32_e32 vcc, v0, v21
	v_mov_b32_e32 v79, 0
	s_nop 0
	v_cndmask_b32_e32 v0, v191, v0, vcc
	v_lshlrev_b32_e32 v217, 2, v0
	ds_bpermute_b32 v23, v217, v3
	ds_bpermute_b32 v22, v217, v2
	v_xor_b32_e32 v0, 32, v191
	v_cmp_lt_i32_e32 vcc, v0, v21
	s_waitcnt lgkmcnt(0)
	v_pk_add_f32 v[2:3], v[2:3], v[22:23]
	v_cndmask_b32_e32 v0, v191, v0, vcc
	v_lshlrev_b32_e32 v219, 2, v0
	ds_bpermute_b32 v23, v219, v3
	ds_bpermute_b32 v22, v219, v2
	s_waitcnt lgkmcnt(0)
	v_pk_add_f32 v[2:3], v[2:3], v[22:23]
	s_nop 0
	v_div_scale_f32 v0, s[18:19], v3, v3, 1.0
	v_rcp_f32_e32 v22, v0
	s_nop 0
	v_fma_f32 v23, -v0, v22, 1.0
	v_fmac_f32_e32 v22, v23, v22
	v_div_scale_f32 v23, vcc, 1.0, v3, 1.0
	v_mul_f32_e32 v24, v23, v22
	v_fma_f32 v25, -v0, v24, v23
	v_fmac_f32_e32 v24, v25, v22
	v_fma_f32 v0, -v0, v24, v23
	v_div_fmas_f32 v0, v0, v22, v24
	v_div_scale_f32 v22, s[18:19], v2, v2, 1.0
	v_rcp_f32_e32 v23, v22
	v_div_fixup_f32 v0, v0, v3, 1.0
	v_cmp_lt_f32_e32 vcc, 0, v3
	s_nop 1
	v_cndmask_b32_e32 v68, 0, v0, vcc
	v_fma_f32 v0, -v22, v23, 1.0
	v_fmac_f32_e32 v23, v0, v23
	v_div_scale_f32 v0, vcc, 1.0, v2, 1.0
	v_mul_f32_e32 v3, v0, v23
	v_fma_f32 v24, -v22, v3, v0
	v_fmac_f32_e32 v3, v24, v23
	v_fma_f32 v0, -v22, v3, v0
	v_div_fmas_f32 v0, v0, v23, v3
	v_lshlrev_b32_e32 v22, 2, v20
	v_lshrrev_b32_e32 v23, 1, v20
	v_and_b32_e32 v22, 16, v22
	v_and_b32_e32 v23, 12, v23
	v_and_b32_e32 v24, 35, v20
	v_or3_b32 v22, v22, v24, v23
	v_lshlrev_b32_e32 v23, 7, v22
	v_lshrrev_b32_e32 v22, 1, v22
	v_xor_b32_e32 v22, v22, v28
	v_lshlrev_b32_e32 v22, 4, v22
	v_and_b32_e32 v22, 0x70, v22
	v_lshlrev_b32_e32 v20, 7, v20
	v_bitop3_b32 v24, v29, s91, v28 bitop3:0x48
	v_add3_u32 v22, 0, v23, v22
	v_add3_u32 v20, 0, v20, v24
	v_div_fixup_f32 v0, v0, v2, 1.0
	v_cmp_lt_f32_e32 vcc, 0, v2
	s_waitcnt vmcnt(0)
	v_xor_b32_e32 v20, 1, v191
	v_cndmask_b32_e32 v70, 0, v0, vcc
	v_cmp_lt_i32_e32 vcc, v20, v21
	v_mov_b32_e32 v2, v1
	v_mov_b32_e32 v3, v1
	v_cndmask_b32_e32 v20, v191, v20, vcc
	v_lshlrev_b32_e32 v77, 2, v20
	v_xor_b32_e32 v20, 2, v191
	v_cmp_lt_i32_e32 vcc, v20, v21
	v_mov_b32_e32 v0, v1
	v_mov_b64_e32 v[38:39], v[2:3]
	v_cndmask_b32_e32 v20, v191, v20, vcc
	v_lshlrev_b32_e32 v78, 2, v20
	v_mov_b64_e32 v[22:23], v[2:3]
	v_mov_b64_e32 v[46:47], v[2:3]
	v_mov_b64_e32 v[30:31], v[2:3]
	v_mov_b64_e32 v[50:51], v[2:3]
	v_mov_b64_e32 v[34:35], v[2:3]
	v_mov_b64_e32 v[26:27], v[2:3]
	v_mov_b64_e32 v[42:43], v[2:3]
	v_mov_b32_e32 v69, v68
	v_mov_b32_e32 v71, v70
	v_mov_b64_e32 v[36:37], v[0:1]
	v_mov_b64_e32 v[20:21], v[0:1]
	v_mov_b64_e32 v[44:45], v[0:1]
	v_mov_b64_e32 v[28:29], v[0:1]
	v_mov_b64_e32 v[48:49], v[0:1]
	v_mov_b64_e32 v[32:33], v[0:1]
	v_mov_b64_e32 v[24:25], v[0:1]
	v_mov_b64_e32 v[40:41], v[0:1]
	v_mov_b32_e32 v3, 0
	s_waitcnt lgkmcnt(0)
	s_barrier
.LBB0_1139:
	s_add_i32 s29, s16, 1
	s_cmp_lt_u32 s29, s28
	v_mov_b32_e32 v2, v189
	s_cselect_b64 s[18:19], -1, 0
	s_cmp_ge_u32 s29, s28
	s_cbranch_scc1 .LBB0_1141
	s_lshl_b32 s17, s29, 1
	s_lshl_b32 s37, s29, 15
	s_and_b32 s37, s37, 0x8000
	s_add_i32 s45, s37, s44
	s_min_i32 s36, s17, s27
	s_add_i32 m0, s45, 0x0
	s_lshl_b32 s98, s36, 13
	s_add_u32 s98, s20, s98
	s_addc_u32 s99, s21, 0
	global_load_lds_dwordx4 v185, s[98:99]
	s_add_i32 m0, s45, 0x2000
	s_lshl_b32 s100, s36, 7
	s_add_u32 s100, s22, s100
	s_addc_u32 s101, s23, 0
	global_load_lds_dwordx4 v198, s[100:101]
	s_add_i32 s36, s17, 1
	s_min_i32 s36, s36, s27
	s_add_i32 m0, s45, 0x4000
	s_lshl_b32 s98, s36, 13
	s_add_u32 s98, s20, s98
	s_addc_u32 s99, s21, 0
	global_load_lds_dwordx4 v185, s[98:99]
	s_add_i32 m0, s45, 0x6000
	s_lshl_b32 s100, s36, 7
	s_add_u32 s100, s22, s100
	s_addc_u32 s101, s23, 0
	global_load_lds_dwordx4 v198, s[100:101]

; template <int STG, class F>
; __device__ __forceinline__ void stream_tiles(Ctx& C, const TileSrc& src, int tile0, int ntiles, LAS unsigned char* bufs, F&& compute) {
;     ...
;         if (more) {
; #pragma unroll
;             for (int h = 0; h < STG; ++h) tile_store(bufs + ((st + 1) & 1) * (STG * 16384) + h * 16384, tidl, rk[h], rv[h]); }
;         __syncthreads();
.LBB0_1148:
	s_andn2_b64 vcc, exec, s[18:19]
	s_cbranch_vccnz .LBB0_1150
	s_waitcnt vmcnt(0) lgkmcnt(0)
